# v022 + SWA units rebalanced: every workgroup 128..255 takes two SWA units
# speedup vs baseline: 1.0118x; 1.0118x over previous
; __global__ void __launch_bounds__(512, 2) hybrid_fwd(Params p) {
;     ...
;             __syncthreads();
;                 if (cc < 64) {
;                     const int u = cc + 128;
;                     const int v = u - 128, hh = v >> 4, e = (v & 15) * 512 + tid, dk = tid & 63;
;                     float* kp = KVB + (size_t)hh * 128 * 8192 + e; const float* dp = DEC + (size_t)hh * 128 * 64 + dk;
.LBB0_549:
	s_or_b64 exec, exec, s[4:5]
	s_add_i32 s12, s2, 0xffffff80
	s_cmpk_lt_i32 s2, 0xc0
	s_cselect_b64 s[0:1], -1, 0
	s_mov_b32 s13, 2
	s_and_b64 vcc, exec, s[0:1]
	s_waitcnt lgkmcnt(0)
	s_barrier
	s_cbranch_vccz .LBB0_555
	s_lshl_b32 s4, s2, 9
	s_and_b32 s4, s4, 0x1e00
	s_lshr_b32 s72, s12, 4
	v_add_u32_e32 v0, s4, v144
	v_and_b32_e32 v2, 63, v144
	s_lshl_b64 s[4:5], s[72:73], 22
	v_ashrrev_i32_e32 v1, 31, v0
	s_lshl_b64 s[6:7], s[72:73], 15
	v_lshl_add_u64 v[0:1], v[0:1], 2, s[4:5]
	v_lshl_or_b32 v2, v2, 2, s6
	v_mov_b32_e32 v3, s7
	v_mov_b32_e32 v58, 0
	s_movk_i32 s4, 0xffe0

; __global__ void __launch_bounds__(512, 2) hybrid_fwd(Params p) {
;     ...
;                 for (int si = 0; si < (cc < 64 ? 1 : 3); ++si) {
;                     const int su = cc < 64 ? cc : 64 + (cc - 64) * 3 + si;
;                     const int v = su, kvh = v >> 7, n = (v >> 1) & 63, pr = v & 1;
;                     const int hl = wave >> 2, qh = kvh * 4 + pr * 2 + hl, tq0 = 128 * n + 32 * (wave & 3), t_row = tq0 + (lane & 31);
;                     attn_unit<1>(lds, tid, PROJ + (size_t)t_row * NP + PJ_SQ + qh * 128, PROJ + PJ_SK + kvh * 128, NP, VT + (size_t)(VT_S + kvh * 128) * T_, T_,
.LBB0_554:
	s_or_b64 exec, exec, s[4:5]
	s_mov_b32 s13, 2
.LBB0_555:
	s_lshl_b32 s14, s2, 1
	s_lshl_b32 s4, s3, 5
	s_addk_i32 s14, 0xff00
	s_ashr_i32 s15, s15, 8
	s_and_b32 s16, s4, 0x60
	s_add_u32 s17, s8, 0x1f601000
	s_addc_u32 s18, s9, 0
	s_add_u32 s19, s8, 0x22f00000
	v_readlane_b32 s4, v255, 42
	v_and_b32_e32 v145, 31, v144
	s_addc_u32 s21, s9, 0
	s_lshl_b32 s22, s4, 3
	s_mov_b32 s23, 0
	v_readlane_b32 s5, v255, 43
	s_branch .LBB0_558

; #define LAS __attribute__((address_space(3)))
; __device__ __forceinline__ float bflo(unsigned w) { return __uint_as_float(w << 16); }
; __device__ __forceinline__ float bfhi(unsigned w) { return __uint_as_float(w & 0xffff0000u); }
;     ...
;     bf16x8 qf[8];
; #pragma unroll
;     for (int ks = 0; ks < 8; ++ks) qf[ks] = *(const bf16x8*)(Qrow + 16 * ks + 8 * hh);
;     f32x16 o[4];
; #pragma unroll
;     for (int db = 0; db < 4; ++db)
; #pragma unroll
;         for (int i = 0; i < 16; ++i) o[db][i] = 0.f;
;     float m = m_init, l = (hh == 0) ? l_init : 0.f;
;     const int pr = (r & ~12) | ((r & 4) << 1) | ((r & 8) >> 1);
;     const unsigned koff = pr * AT_KROW + 16 * hh, voff = AT_KBUF + r * AT_VROW + 16 * hh;
;     const int kkey0 = tid >> 4, kc16 = tid & 15, vd0 = tid >> 3, vc8 = tid & 7;
;     u32x4 kreg[2], vreg[2]; float creg = 0.f;
;     ...
;     float qn = 0.f; bool wdone = false;
;     LAS unsigned* flg = (LAS unsigned*)(lds + 2 * AT_BUF);
;     if (MODE == 0) {
; #pragma unroll
;         for (int ks = 0; ks < 8; ++ks) { const u32x4 qq = __builtin_bit_cast(u32x4, qf[ks]);
;             qn += bflo(qq.x) * bflo(qq.x) + bfhi(qq.x) * bfhi(qq.x) + bflo(qq.y) * bflo(qq.y) + bfhi(qq.y) * bfhi(qq.y) + bflo(qq.z) * bflo(qq.z) + bfhi(qq.z) * bfhi(qq.z) + bflo(qq.w) * bflo(qq.w) + bfhi(qq.w) * bfhi(qq.w); }
;         qn = xsum(qn); qn = sqrtf(qn) * kn * SC * 1.0001f + 1e-3f;
;     }
;     AT_LOAD(kt1 - 1); AT_WRITE(0); __syncthreads();
; __global__ void __launch_bounds__(512, 2) hybrid_fwd(Params p) {
;     ...
;                 for (int si = 0; si < (cc < 64 ? 1 : 3); ++si) {
;                     const int su = cc < 64 ? cc : 64 + (cc - 64) * 3 + si;
;                     const int v = su, kvh = v >> 7, n = (v >> 1) & 63, pr = v & 1;
;                     const int hl = wave >> 2, qh = kvh * 4 + pr * 2 + hl, tq0 = 128 * n + 32 * (wave & 3), t_row = tq0 + (lane & 31);
;                     attn_unit<1>(lds, tid, PROJ + (size_t)t_row * NP + PJ_SQ + qh * 128, PROJ + PJ_SK + kvh * 128, NP, VT + (size_t)(VT_S + kvh * 128) * T_, T_,
;                                  (2 * n - 2) < 0 ? 0 : (2 * n - 2), 2 * n + 2, t_row, tq0, nullptr, p.swa_sinks[l * 8 + qh] * LOG2E, 1.f, t5 + qh * 128,
;                                  O + (size_t)t_row * D_ + 512 + qh * 128);
.LBB0_558:
	s_add_i32 s6, s14, s23
	s_and_b64 s[4:5], exec, s[0:1]
	s_nop 0
	s_bfe_u32 s24, s6, 0x60001
	s_ashr_i32 s4, s6, 5
	s_lshl_b32 s5, s6, 1
	s_lshl_b32 s72, s24, 7
	s_and_b32 s4, s4, -4
	s_and_b32 s5, s5, 2
	s_or_b32 s28, s72, s16
	s_or_b32 s4, s4, s5
	v_or_b32_e32 v160, s28, v145
	v_mov_b64_e32 v[0:1], s[8:9]
	s_add_i32 s25, s4, s15
	v_mad_u64_u32 v[146:147], s[4:5], v160, s56, v[0:1]
	s_and_b32 s10, s6, 0xffffff80
	s_lshl_b32 s4, s25, 7
	s_ashr_i32 s11, s10, 31
	s_ashr_i32 s5, s4, 31
	s_lshl_b64 s[6:7], s[10:11], 1
	s_add_u32 s26, s17, s6
	s_addc_u32 s27, s18, s7
	s_lshl_b64 s[10:11], s[10:11], 14
	s_add_u32 s10, s19, s10
	s_addc_u32 s11, s21, s11
	s_lshl_b32 s29, s24, 1
	s_add_i32 s30, s29, -2
	s_cmp_lg_u32 s24, 0
	s_cselect_b32 s24, s30, 0
	s_add_i32 s30, s25, s22
	s_ashr_i32 s31, s30, 31
	s_lshl_b64 s[30:31], s[30:31], 2
	s_add_u32 s30, s60, s30
	s_addc_u32 s31, s61, s31
	v_mov_b32_e32 v5, v144
	global_load_dword v4, v201, s[30:31]
	v_lshl_add_u64 v[0:1], s[4:5], 1, v[146:147]
	v_bfe_u32 v161, v5, 5, 1
	v_lshlrev_b32_e32 v200, 4, v161
	v_lshl_add_u64 v[0:1], v[0:1], 0, v[200:201]
	s_mov_b32 s25, 0x1f600000
	s_mov_b64 s[30:31], 0x1f600800
	v_add_co_u32_e32 v10, vcc, s25, v0
	v_ashrrev_i32_e32 v6, 4, v5
	s_or_b32 s25, s29, 1
	v_lshl_add_u64 v[8:9], v[0:1], 0, s[30:31]
	v_addc_co_u32_e32 v11, vcc, 0, v1, vcc
	v_lshl_add_u32 v13, s25, 6, v6
	v_mov_b64_e32 v[0:1], s[26:27]
	v_mad_i64_i32 v[2:3], s[26:27], v13, s56, v[0:1]
	v_lshlrev_b32_e32 v14, 4, v5
	v_add_u32_e32 v13, 32, v13
	v_ashrrev_i32_e32 v12, 3, v5
	v_and_b32_e32 v148, 0xf0, v14
	v_mov_b32_e32 v149, v201
	v_mad_i64_i32 v[0:1], s[26:27], v13, s56, v[0:1]
	flat_load_dwordx4 v[96:99], v[8:9] offset:32
	flat_load_dwordx4 v[100:103], v[8:9] offset:64
	flat_load_dwordx4 v[104:107], v[8:9] offset:96
	flat_load_dwordx4 v[108:111], v[8:9] offset:128
	v_lshl_add_u64 v[2:3], v[2:3], 0, v[148:149]
	v_lshl_add_u64 v[0:1], v[0:1], 0, v[148:149]
	v_ashrrev_i32_e32 v13, 31, v12
	s_nop 0
	flat_load_dwordx4 v[112:115], v[2:3]
	flat_load_dwordx4 v[116:119], v[0:1]
	v_lshlrev_b64 v[0:1], 14, v[12:13]
	v_lshl_add_u64 v[2:3], s[10:11], 0, v[0:1]
	s_mov_b64 s[10:11], 0x800000
	v_and_b32_e32 v7, 7, v5
	v_lshl_add_u64 v[0:1], v[2:3], 0, s[10:11]
	s_lshl_b32 s10, s25, 7
	s_mov_b32 s11, s73
	s_mov_b64 s[26:27], 0x900000
	v_lshl_add_u64 v[14:15], v[0:1], 0, s[10:11]
	v_lshlrev_b32_e32 v150, 4, v7
	v_mov_b32_e32 v151, v201
	v_lshl_add_u64 v[2:3], v[2:3], 0, s[26:27]
	v_lshl_add_u64 v[14:15], v[14:15], 0, v[150:151]
	v_lshl_add_u64 v[16:17], v[2:3], 0, s[10:11]
	v_lshl_add_u64 v[16:17], v[16:17], 0, v[150:151]
	flat_load_dwordx4 v[136:139], v[14:15]
	flat_load_dwordx4 v[140:143], v[16:17]
	flat_load_dwordx4 v[120:123], v[8:9] offset:160
	flat_load_dwordx4 v[124:127], v[8:9] offset:192
	flat_load_dwordx4 v[128:131], v[10:11] offset:2048
	flat_load_dwordx4 v[132:135], v[8:9] offset:224
	s_movk_i32 s10, 0x110
	v_cmp_eq_u32_e32 vcc, 0, v161
	v_mul_lo_u32 v151, v6, s10
	v_mov_b32_e32 v15, 0
	s_cmp_lt_u32 s29, s24
	v_cndmask_b32_e64 v149, 0, 1.0, vcc
	v_mul_lo_u32 v162, v12, s83
	v_add3_u32 v8, 0, v151, v148
	v_add3_u32 v9, 0, v162, v150
	s_waitcnt vmcnt(0) lgkmcnt(0)
	ds_write_b128 v8, v[112:115]
	ds_write_b128 v8, v[116:119] offset:8704
	ds_write_b128 v9, v[136:139] offset:17408
	ds_write_b128 v9, v[140:143] offset:26624
	s_waitcnt lgkmcnt(0)
	s_barrier
	s_cbranch_scc1 .LBB0_556
	v_and_b32_e32 v8, 31, v5
	v_and_b32_e32 v9, 19, v5
	v_lshlrev_b32_e32 v10, 1, v5
	v_lshrrev_b32_e32 v5, 1, v5
	v_and_b32_e32 v10, 8, v10
	v_and_b32_e32 v5, 4, v5
	v_lshlrev_b32_e32 v7, 3, v7
	v_or3_b32 v5, v9, v10, v5
	v_mul_u32_u24_e32 v163, 0x90, v8
	s_lshl_b32 s10, s4, 2
	v_lshlrev_b32_e32 v8, 1, v7
	v_mov_b32_e32 v9, v201
	s_add_i32 s26, s10, 0
	v_lshl_add_u64 v[152:153], v[0:1], 0, v[8:9]
	v_lshl_add_u64 v[154:155], v[2:3], 0, v[8:9]
	v_mov_b32_e32 v0, s16
	s_movk_i32 s10, 0x78
	v_add_u32_e32 v2, s72, v6
	s_add_i32 s26, s26, 0x12000
	s_or_b32 s27, s28, 31
	s_addk_i32 s28, 0xff80
	v_mad_u32_u24 v167, v161, s10, v0
	v_add_u32_e32 v0, 32, v2
	v_mad_i64_i32 v[0:1], s[10:11], v0, s56, 0
	s_add_u32 s6, s17, s6
	v_or_b32_e32 v0, v0, v148
	s_addc_u32 s7, s18, s7
	v_lshl_add_u64 v[156:157], s[6:7], 0, v[0:1]
	v_mad_i64_i32 v[0:1], s[10:11], v2, s56, 0
	v_mul_u32_u24_e32 v5, 0x110, v5
	v_or_b32_e32 v0, v0, v148
	v_mov_b32_e32 v48, 0
	v_add_u32_e32 v164, v5, v200
	v_add_u32_e32 v165, 0x2400, v162
	v_mul_f32_e32 v168, 0x3fb8aa3b, v4
	v_mad_i32_i24 v166, v161, -8, s16
	v_lshl_add_u64 v[158:159], s[6:7], 0, v[0:1]
	v_mov_b32_e32 v49, v48
	v_mov_b32_e32 v50, v48
	v_mov_b32_e32 v51, v48
	v_mov_b32_e32 v52, v48
	v_mov_b32_e32 v53, v48
	v_mov_b32_e32 v54, v48
	v_mov_b32_e32 v55, v48
	v_mov_b32_e32 v56, v48
	v_mov_b32_e32 v57, v48
	v_mov_b32_e32 v58, v48
	v_mov_b32_e32 v59, v48
	v_mov_b32_e32 v60, v48
	v_mov_b32_e32 v61, v48
	v_mov_b32_e32 v62, v48
	v_mov_b32_e32 v63, v48
	v_mov_b32_e32 v32, v48
	v_mov_b32_e32 v33, v48
	v_mov_b32_e32 v34, v48
	v_mov_b32_e32 v35, v48
	v_mov_b32_e32 v36, v48
	v_mov_b32_e32 v37, v48
	v_mov_b32_e32 v38, v48
	v_mov_b32_e32 v39, v48
	v_mov_b32_e32 v40, v48
	v_mov_b32_e32 v41, v48
	v_mov_b32_e32 v42, v48
	v_mov_b32_e32 v43, v48
	v_mov_b32_e32 v44, v48
	v_mov_b32_e32 v45, v48
	v_mov_b32_e32 v46, v48
	v_mov_b32_e32 v47, v48
	v_mov_b32_e32 v16, v48
	v_mov_b32_e32 v17, v48
	v_mov_b32_e32 v18, v48
	v_mov_b32_e32 v19, v48
	v_mov_b32_e32 v20, v48
	v_mov_b32_e32 v21, v48
	v_mov_b32_e32 v22, v48
	v_mov_b32_e32 v23, v48
	v_mov_b32_e32 v24, v48
	v_mov_b32_e32 v25, v48
	v_mov_b32_e32 v26, v48
	v_mov_b32_e32 v27, v48
	v_mov_b32_e32 v28, v48
	v_mov_b32_e32 v29, v48
	v_mov_b32_e32 v30, v48
	v_mov_b32_e32 v31, v48
	v_mov_b32_e32 v0, v48
	v_mov_b32_e32 v1, v48
	v_mov_b32_e32 v2, v48
	v_mov_b32_e32 v3, v48
	v_mov_b32_e32 v4, v48
	v_mov_b32_e32 v5, v48
	v_mov_b32_e32 v6, v48
	v_mov_b32_e32 v7, v48
	v_mov_b32_e32 v8, v48
	v_mov_b32_e32 v9, v48
	v_mov_b32_e32 v10, v48
	v_mov_b32_e32 v11, v48
	v_mov_b32_e32 v12, v48
	v_mov_b32_e32 v13, v48
	v_mov_b32_e32 v14, v48
	v_mov_b32_e32 v15, v48
	s_branch .LBB0_561
